# attention unit prologue: bias-table load no longer waited for before the Q / first K,V tile loads are issued
# speedup vs baseline: 1.0019x; 1.0019x over previous
.LBB0_218:
	s_bfe_u32 s4, s36, 0x30004
	v_lshl_add_u32 v0, s4, 9, v222
	v_ashrrev_i32_e32 v1, 31, v0
	v_lshl_add_u64 v[0:1], v[0:1], 2, s[14:15]
	global_load_dword v232, v[0:1], off
	s_lshl_b32 s5, s36, 6
	s_and_b32 s66, s5, 0x2000
	s_lshl_b32 s5, s21, 7
	s_add_i32 s5, s5, s58
	s_ashr_i32 s8, s5, 31
	s_add_u32 s62, s5, s66
	s_addc_u32 s63, s8, 0
	v_mov_b32_e32 v1, s63
	s_lshl_b32 s89, s4, 7
	s_lshl_b32 s4, s4, 8
	s_mov_b32 s5, s67
	s_mov_b32 s65, s67
	v_lshl_add_u64 v[2:3], s[66:67], 0, v[146:147]
	v_lshlrev_b64 v[2:3], 10, v[2:3]
	v_mov_b32_e32 v5, v3
	v_add_u32_e32 v20, 0, v159
	s_cmp_eq_u32 s21, 0


	v_or_b32_e32 v0, s62, v144
	v_lshlrev_b64 v[0:1], 11, v[0:1]
	v_lshl_add_u64 v[0:1], s[46:47], 0, v[0:1]
	v_lshl_add_u64 v[0:1], v[0:1], 0, s[4:5]
	v_lshl_add_u64 v[0:1], v[0:1], 0, s[64:65]
	v_lshl_add_u64 v[0:1], v[0:1], 0, v[208:209]
	global_load_dwordx4 v[112:115], v[0:1], off
	global_load_dwordx4 v[116:119], v[0:1], off offset:32
	global_load_dwordx4 v[120:123], v[0:1], off offset:64
	global_load_dwordx4 v[124:127], v[0:1], off offset:96
	v_or_b32_e32 v0, s89, v148
	v_or_b32_e32 v4, v2, v0
	v_lshlrev_b64 v[12:13], 1, v[4:5]
	v_lshl_add_u64 v[4:5], s[10:11], 0, v[12:13]
	global_load_dwordx4 v[4:7], v[4:5], off
	v_lshl_add_u64 v[8:9], s[12:13], 0, v[12:13]
	v_add_u32_e32 v1, 0, v157
	global_load_dwordx4 v[8:11], v[8:9], off
	s_mov_b64 s[4:5], 0x10000
	v_lshl_add_u64 v[16:17], v[12:13], 0, s[4:5]
	v_lshl_add_u64 v[12:13], s[10:11], 0, v[16:17]
	global_load_dwordx4 v[12:15], v[12:13], off
	v_lshl_add_u64 v[16:17], s[12:13], 0, v[16:17]
	global_load_dwordx4 v[16:19], v[16:17], off
	s_waitcnt vmcnt(3)
	ds_write_b32 v149, v232
	ds_write_b128 v1, v[4:7]
	v_lshl_add_u64 v[4:5], s[66:67], 0, v[150:151]
	v_lshlrev_b64 v[4:5], 11, v[4:5]
	v_lshl_or_b32 v4, v0, 1, v4
	v_lshl_add_u64 v[6:7], s[10:11], 0, v[4:5]
	global_load_dwordx4 v[128:131], v[6:7], off
	v_lshl_add_u64 v[6:7], s[12:13], 0, v[4:5]
	v_lshl_add_u64 v[4:5], v[4:5], 0, s[4:5]
	global_load_dwordx4 v[132:135], v[6:7], off
	v_lshl_add_u64 v[6:7], s[10:11], 0, v[4:5]
	v_lshl_add_u64 v[4:5], s[12:13], 0, v[4:5]
	global_load_dwordx4 v[136:139], v[6:7], off
	global_load_dwordx4 v[140:143], v[4:5], off
	s_waitcnt vmcnt(6)
	ds_write_b128 v20, v[8:11] offset:34816
	v_add_u32_e32 v8, 0, v161
	v_add_u32_e32 v9, 0, v163
	s_waitcnt vmcnt(5)
	ds_write_b128 v8, v[12:15]
	s_waitcnt vmcnt(4)
	ds_write_b128 v9, v[16:19] offset:34816
	s_waitcnt lgkmcnt(0)
	s_barrier
	s_waitcnt vmcnt(3)
	ds_write_b128 v1, v[128:131] offset:17408
	s_waitcnt vmcnt(2)
	ds_write_b128 v20, v[132:135] offset:55296
	s_waitcnt vmcnt(1)
	ds_write_b128 v8, v[136:139] offset:17408
	s_waitcnt vmcnt(0)
	ds_write_b128 v9, v[140:143] offset:55296
	s_cbranch_scc1 .LBB0_220
	v_mov_b32_e32 v1, v209
	v_lshl_add_u64 v[2:3], v[2:3], 0, s[78:79]
	v_or_b32_e32 v4, v2, v0
	v_mov_b32_e32 v5, v3
	v_lshl_add_u64 v[0:1], v[2:3], 0, v[0:1]
	v_lshlrev_b64 v[4:5], 1, v[4:5]
	v_lshl_add_u64 v[0:1], v[0:1], 1, v[214:215]
	v_lshl_add_u64 v[6:7], s[10:11], 0, v[4:5]
	v_lshl_add_u64 v[2:3], s[10:11], 0, v[0:1]
	v_lshl_add_u64 v[4:5], s[12:13], 0, v[4:5]
	global_load_dwordx4 v[128:131], v[6:7], off
	global_load_dwordx4 v[132:135], v[4:5], off
	v_lshl_add_u64 v[0:1], s[12:13], 0, v[0:1]
	global_load_dwordx4 v[136:139], v[2:3], off
	global_load_dwordx4 v[140:143], v[0:1], off
